# attention loop: unit-start vmcnt(0) relaxed to vmcnt(4) (no wait on the previous unit's O stores), vmcnt(12) after the prefetch issue removed; snake MFMA order
# speedup vs baseline: 1.0075x; 1.0016x over previous
; __device__ __forceinline__ void attn_phase(LAS unsigned char* lds, const bf16_t* qp, const bf16_t* kvp, bf16_t* obuf, float* lse, const float* biasG, const int gi, const int rsh, const int G) {
;     ...
;         const int wbase = j == 0 ? 0 : ((2 * j + 1) % 3) * 128;
; #pragma unroll
;         for (int it = 0; it < 6; ++it) {
;             const int idx = tid + 512 * it, kl = idx >> 3, ch = idx & 7;
;             if (j == 0 || it < 4) {
;                 int row = wbase + kl; row = row >= 384 ? row - 384 : row;
;                 const bool pre = (np == 0) && (j == 0) && (kl < 128);
;                 const u32x4 z4 = (u32x4){0u, 0u, 0u, 0u};
;                 *(LAS u32x4*)(lds + A_K0 + ch * KCS + row * 16) = pre ? z4 : kr[it];
;                 *(LAS u32x4*)(lds + A_V0 + (ch >> 2) * VHS + row * 64 + (ch & 3) * 16) = pre ? z4 : vr[it];
;             }
;         }
;         bf16x8 qr[4];
; #pragma unroll
;         for (int d0 = 0; d0 < 4; ++d0) qr[d0] = qn[d0];
;         asm volatile("s_waitcnt lgkmcnt(0)\n\ts_barrier" ::: "memory");
;         const int nu = ((unit + 1) & (RL - 1)) ? unit + 1 : unit + 1 + (G - 1) * RL; const bool has_next = nu < 2048;
;         const int mq = 256 * np + 32 * w + r32; const size_t growq = rowb + ((size_t)mq << rsh) + s;
;         float lp = 0.f; if (gi > 0) lp = gld<float>(lse + growq * 16 + h);
;         if (has_next) attn_load(qp, kvp, biasG, rsh, nu, tid, w, r32, hi, kr, vr, qn, bn);
;         const int c0 = ((2 * j) % 3) * 4 + w;
;         int sc[5];
; #pragma unroll
;         for (int cc = 0; cc < 5; ++cc) { const int t = c0 + cc; sc[cc] = t >= 12 ? t - 12 : t; }
;         f32x16 p[5];
;         const LAS float* bt = (const LAS float*)(lds + A_BT);
;         const LAS unsigned char* kbase = lds + A_K0 + hi * KCS + r32 * 16;
; #pragma unroll
;         for (int c2 = 0; c2 < 5; c2 += 2) {
;             bf16x8 ka[4], kb[4];
; #pragma unroll
;             for (int d0 = 0; d0 < 4; ++d0) { ka[d0] = *(const LAS bf16x8*)(kbase + 2 * d0 * KCS + sc[c2] * 512); if (c2 + 1 < 5) kb[d0] = *(const LAS bf16x8*)(kbase + 2 * d0 * KCS + sc[c2 + 1 < 5 ? c2 + 1 : c2] * 512); }
; #pragma unroll
;             for (int q = 0; q < 2; ++q) { const int cc = c2 + q; if (cc < 5) { const bool dead = (np == 0) && (w + cc < 4);
;                 const LAS float* bq_ = dead ? bt + 27 - (160 + r32 - 32 * cc - 4 * hi) : bt;
; #pragma unroll
.LBB0_97:
	s_xor_b64 s[12:13], s[0:1], -1
	v_readlane_b32 s0, v253, 2
	s_mul_i32 s11, s11, s0
	v_and_b32_e32 v6, 7, v0
	s_movk_i32 s0, 0x1810
	v_lshlrev_b32_e32 v5, 3, v3
	v_mad_u32_u24 v239, v6, s0, 0
	v_readlane_b32 s0, v255, 25
	v_lshlrev_b32_e32 v190, 1, v5
	v_mov_b32_e32 v191, v96
	v_readlane_b32 s1, v255, 26
	v_or_b32_e32 v241, s3, v238
	s_add_u32 s16, s54, 0x6e00000
	v_lshl_add_u64 v[192:193], s[0:1], 0, v[190:191]
	v_readlane_b32 s0, v254, 37
	v_cmp_eq_u32_e32 vcc, 0, v3
	s_addc_u32 s17, s55, 0
	v_lshl_add_u32 v242, v0, 2, s0
	s_movk_i32 s0, 0x80
	v_cmp_gt_i32_e64 s[2:3], s0, v97
	s_and_b64 s[98:99], s[24:25], vcc
	v_lshl_add_u64 v[194:195], v[0:1], 2, s[28:29]
	v_writelane_b32 v255, s2, 33
	v_mul_u32_u24_e32 v1, 0x1810, v3
	v_lshlrev_b32_e32 v5, 4, v238
	v_writelane_b32 v255, s3, 34
	v_cmp_gt_i32_e64 s[2:3], s0, v180
	v_cmp_gt_i32_e64 s[48:49], s0, v235
	s_cmp_lt_i32 s10, 4
	v_writelane_b32 v255, s2, 29
	v_add3_u32 v243, 0, v1, v5
	v_lshlrev_b32_e32 v1, 2, v3
	v_writelane_b32 v255, s3, 30
	v_cmp_gt_i32_e64 s[2:3], s0, v234
	s_cselect_b64 s[52:53], -1, 0
	s_cmp_lt_i32 s10, 3
	v_writelane_b32 v255, s2, 19
	v_lshlrev_b32_e32 v4, 3, v0
	v_bfe_u32 v6, v0, 2, 1
	v_writelane_b32 v255, s3, 20
	v_cmp_gt_i32_e64 s[2:3], s0, v236
	v_cmp_gt_i32_e64 s[0:1], s0, v237
	v_sub_u32_e32 v1, v1, v238
	v_writelane_b32 v255, s2, 17
	v_lshlrev_b32_e32 v0, 1, v0
	s_cselect_b64 s[50:51], -1, 0
	v_writelane_b32 v255, s3, 18
	v_writelane_b32 v255, s0, 40
	s_cmp_lt_i32 s10, 2
	v_and_b32_e32 v0, 32, v0
	v_writelane_b32 v255, s1, 41
	v_readlane_b32 s0, v254, 38
	v_and_b32_e32 v4, 24, v4
	v_mul_u32_u24_e32 v6, 0x6040, v6
	v_lshl_add_u32 v245, v1, 2, s0
	s_cselect_b64 s[0:1], -1, 0
	s_cmp_lt_i32 s10, 1
	v_and_b32_e32 v7, 48, v2
	v_mul_i32_i24_e32 v5, -4, v3
	v_add3_u32 v0, 0, v0, v4
	v_lshlrev_b32_e32 v4, 8, v3
	v_and_b32_e32 v2, 0xc0, v2
	s_cselect_b64 s[42:43], -1, 0
	s_cmp_lt_i32 s10, 0
	v_add3_u32 v240, 0, v6, v7
	v_add3_u32 v244, v0, v4, v2
	v_add_u32_e32 v246, 0x80, v245
	v_add_u32_e32 v247, 0x100, v245
	v_add_u32_e32 v248, 0x180, v245
	s_cselect_b64 s[44:45], -1, 0
	v_add_u32_e32 v249, 0x200, v245
	v_lshlrev_b32_e32 v250, 2, v5
	s_waitcnt vmcnt(0)
	s_branch .LBB0_100

; #define LAS __attribute__((address_space(3)))
; __device__ __forceinline__ void attn_phase(LAS unsigned char* lds, const bf16_t* qp, const bf16_t* kvp, bf16_t* obuf, float* lse, const float* biasG, const int gi, const int rsh, const int G) {
;     ...
;         if (tid < 192) ((LAS float*)(lds + A_BT))[tid] = bn;
.LBB0_100:
	s_and_saveexec_b64 s[24:25], s[40:41]
	s_cbranch_execz .LBB0_102
	s_waitcnt vmcnt(4)
	ds_write_b32 v242, v181

; #define LAS __attribute__((address_space(3)))
; __device__ __forceinline__ void attn_phase(LAS unsigned char* lds, const bf16_t* qp, const bf16_t* kvp, bf16_t* obuf, float* lse, const float* biasG, const int gi, const int rsh, const int G) {
;     ...
;         const int wbase = j == 0 ? 0 : ((2 * j + 1) % 3) * 128;
; #pragma unroll
;         for (int it = 0; it < 6; ++it) {
;             const int idx = tid + 512 * it, kl = idx >> 3, ch = idx & 7;
;             if (j == 0 || it < 4) {
;                 int row = wbase + kl; row = row >= 384 ? row - 384 : row;
;                 const bool pre = (np == 0) && (j == 0) && (kl < 128);
;                 const u32x4 z4 = (u32x4){0u, 0u, 0u, 0u};
;                 *(LAS u32x4*)(lds + A_K0 + ch * KCS + row * 16) = pre ? z4 : kr[it];
;                 *(LAS u32x4*)(lds + A_V0 + (ch >> 2) * VHS + row * 64 + (ch & 3) * 16) = pre ? z4 : vr[it];
;             }
;         }
.LBB0_104:
	s_cmp_eq_u32 s2, 0
	v_add_u32_e32 v0, s4, v97
	s_movk_i32 s23, 0x17f
	v_readlane_b32 s18, v255, 33
	s_cselect_b64 s[46:47], -1, 0
	v_add_u32_e32 v1, 0xfffffe80, v0
	v_cmp_lt_i32_e32 vcc, s23, v0
	v_readlane_b32 s19, v255, 34
	s_and_b64 s[18:19], s[18:19], s[46:47]
	v_cndmask_b32_e32 v8, v0, v1, vcc
	s_waitcnt vmcnt(4)
	v_cndmask_b32_e64 v3, v101, 0, s[18:19]
	v_cndmask_b32_e64 v2, v100, 0, s[18:19]
	v_cndmask_b32_e64 v1, v99, 0, s[18:19]
	v_cndmask_b32_e64 v0, v98, 0, s[18:19]
	v_lshl_add_u32 v9, v8, 4, v239
	s_waitcnt vmcnt(10)
	v_cndmask_b32_e64 v7, v105, 0, s[18:19]
	v_cndmask_b32_e64 v6, v104, 0, s[18:19]
	v_cndmask_b32_e64 v5, v103, 0, s[18:19]
	v_cndmask_b32_e64 v4, v102, 0, s[18:19]
	ds_write_b128 v9, v[0:3]
	v_lshl_add_u32 v0, v8, 6, v240
	ds_write_b128 v0, v[4:7] offset:49280
	v_add_u32_e32 v0, s4, v180
	v_readlane_b32 s18, v255, 29
	v_add_u32_e32 v1, 0xfffffe80, v0
	v_cmp_lt_i32_e32 vcc, s23, v0
	v_readlane_b32 s19, v255, 30
	s_and_b64 s[18:19], s[18:19], s[46:47]
	v_cndmask_b32_e32 v8, v0, v1, vcc
	s_waitcnt vmcnt(9)
	v_cndmask_b32_e64 v3, v109, 0, s[18:19]
	v_cndmask_b32_e64 v2, v108, 0, s[18:19]
	v_cndmask_b32_e64 v1, v107, 0, s[18:19]
	v_cndmask_b32_e64 v0, v106, 0, s[18:19]
	v_lshl_add_u32 v9, v8, 4, v239
	s_waitcnt vmcnt(8)
	v_cndmask_b32_e64 v7, v113, 0, s[18:19]
	v_cndmask_b32_e64 v6, v112, 0, s[18:19]
	v_cndmask_b32_e64 v5, v111, 0, s[18:19]
	v_cndmask_b32_e64 v4, v110, 0, s[18:19]
	ds_write_b128 v9, v[0:3]
	v_lshl_add_u32 v0, v8, 6, v240
	ds_write_b128 v0, v[4:7] offset:49280
	v_add_u32_e32 v0, s4, v234
	v_readlane_b32 s18, v255, 19
	v_add_u32_e32 v1, 0xfffffe80, v0
	v_cmp_lt_i32_e32 vcc, s23, v0
	v_readlane_b32 s19, v255, 20
	s_and_b64 s[18:19], s[18:19], s[46:47]
	v_cndmask_b32_e32 v8, v0, v1, vcc
	s_waitcnt vmcnt(7)
	v_cndmask_b32_e64 v3, v117, 0, s[18:19]
	v_cndmask_b32_e64 v2, v116, 0, s[18:19]
	v_cndmask_b32_e64 v1, v115, 0, s[18:19]
	v_cndmask_b32_e64 v0, v114, 0, s[18:19]
	v_lshl_add_u32 v9, v8, 4, v239
	s_waitcnt vmcnt(6)
	v_cndmask_b32_e64 v7, v129, 0, s[18:19]
	v_cndmask_b32_e64 v6, v128, 0, s[18:19]
	v_cndmask_b32_e64 v5, v127, 0, s[18:19]
	v_cndmask_b32_e64 v4, v126, 0, s[18:19]
	ds_write_b128 v9, v[0:3]
	v_lshl_add_u32 v0, v8, 6, v240
	ds_write_b128 v0, v[4:7] offset:49280
	v_add_u32_e32 v0, s4, v235
	v_add_u32_e32 v1, 0xfffffe80, v0
	v_cmp_lt_i32_e32 vcc, s23, v0
	s_and_b64 s[18:19], s[48:49], s[46:47]
	s_waitcnt vmcnt(5)
	v_cndmask_b32_e64 v3, v141, 0, s[18:19]
	v_cndmask_b32_e32 v8, v0, v1, vcc
	v_cndmask_b32_e64 v2, v140, 0, s[18:19]
	v_cndmask_b32_e64 v1, v139, 0, s[18:19]
	v_cndmask_b32_e64 v0, v138, 0, s[18:19]
	v_lshl_add_u32 v9, v8, 4, v239
	v_mov_b32_e32 v225, 0x1fcf
	s_waitcnt vmcnt(4)
	v_cndmask_b32_e64 v7, v145, 0, s[18:19]
	v_cndmask_b32_e64 v6, v144, 0, s[18:19]
	v_cndmask_b32_e64 v5, v143, 0, s[18:19]
	v_cndmask_b32_e64 v4, v142, 0, s[18:19]
	ds_write_b128 v9, v[0:3]
	v_lshl_add_u32 v0, v8, 6, v240
	s_andn2_b64 vcc, exec, s[24:25]
	ds_write_b128 v0, v[4:7] offset:49280
	s_cbranch_vccnz .LBB0_106
	v_add_u32_e32 v0, s4, v236
	v_readlane_b32 s18, v255, 17
	v_add_u32_e32 v1, 0xfffffe80, v0
	v_cmp_lt_i32_e32 vcc, s23, v0
	v_readlane_b32 s19, v255, 18
	s_and_b64 s[18:19], s[46:47], s[18:19]
	v_cndmask_b32_e32 v8, v0, v1, vcc
	v_lshl_add_u32 v9, v8, 4, v239
	v_cndmask_b32_e64 v3, v121, 0, s[18:19]
	v_cndmask_b32_e64 v2, v120, 0, s[18:19]
	v_cndmask_b32_e64 v1, v119, 0, s[18:19]
	v_cndmask_b32_e64 v0, v118, 0, s[18:19]
	v_cndmask_b32_e64 v7, v125, 0, s[18:19]
	v_cndmask_b32_e64 v6, v124, 0, s[18:19]
	v_cndmask_b32_e64 v5, v123, 0, s[18:19]
	v_cndmask_b32_e64 v4, v122, 0, s[18:19]
	ds_write_b128 v9, v[0:3]
	v_lshl_add_u32 v0, v8, 6, v240
	ds_write_b128 v0, v[4:7] offset:49280
	v_add_u32_e32 v0, s4, v237
	v_readlane_b32 s18, v255, 40
	v_add_u32_e32 v1, 0xfffffe80, v0
	v_cmp_lt_i32_e32 vcc, s23, v0
	v_readlane_b32 s19, v255, 41
	s_and_b64 s[18:19], s[46:47], s[18:19]
	v_cndmask_b32_e32 v8, v0, v1, vcc
	v_lshl_add_u32 v9, v8, 4, v239
	v_cndmask_b32_e64 v3, v133, 0, s[18:19]
	v_cndmask_b32_e64 v2, v132, 0, s[18:19]
	v_cndmask_b32_e64 v1, v131, 0, s[18:19]
	v_cndmask_b32_e64 v0, v130, 0, s[18:19]
	v_cndmask_b32_e64 v7, v137, 0, s[18:19]
	v_cndmask_b32_e64 v6, v136, 0, s[18:19]
	v_cndmask_b32_e64 v5, v135, 0, s[18:19]
	v_cndmask_b32_e64 v4, v134, 0, s[18:19]
	ds_write_b128 v9, v[0:3]
	v_lshl_add_u32 v0, v8, 6, v240
	ds_write_b128 v0, v[4:7] offset:49280

; __device__ __forceinline__ void attn_load(const bf16_t* qp, const bf16_t* kvp, const float* biasG, const int rsh, const int unit, const int tid, const int w, const int r32, const int hi,
;                                           u32x4 (&kr)[6], u32x4 (&vr)[6], bf16x8 (&qn)[4], float& bn) {
;     ...
;     { const int mq = 256 * np + 32 * w + r32; const bf16_t* p = qp + ((size_t)h * M + rowb + (size_t)s * (SEQ >> rsh) + mq) * 64 + hi * 8;
; #pragma unroll
;       for (int d0 = 0; d0 < 4; ++d0) qn[d0] = gld<bf16x8>(p + 16 * d0); }
;     bn = tid < 192 ? gld<float>(biasG + h * 192 + tid) : 0.f;
.LBB0_111:
	v_add_u32_e32 v0, s3, v241
	v_ashrrev_i32_e32 v1, 31, v0
	v_lshl_add_u64 v[0:1], s[28:29], 0, v[0:1]
	v_lshlrev_b64 v[0:1], 7, v[0:1]
	v_lshl_add_u64 v[0:1], v[192:193], 0, v[0:1]
	global_load_dwordx4 v[162:165], v[0:1], off
	global_load_dwordx4 v[166:169], v[0:1], off offset:32
	global_load_dwordx4 v[170:173], v[0:1], off offset:64
	global_load_dwordx4 v[174:177], v[0:1], off offset:96
	s_nop 0
	v_mov_b32_e32 v181, 0
	s_and_saveexec_b64 s[28:29], s[40:41]
	s_cbranch_execz .LBB0_113
	s_mul_i32 s4, s2, 0x300
	v_lshl_add_u64 v[0:1], v[194:195], 0, s[4:5]
	global_load_dword v181, v[0:1], off
